# baseline (speedup 1.0000x reference)
;     __device__ __forceinline__ void fused(f32x4 (&acc)[2][2][4][2], const pg8::Unit& u, int wr, int wc, int fr, int fq, LAS unsigned char* lds, int wid) const {
;     ...
;         if (lane < 32) { float s = 0.f, q = 0.f;
; #pragma unroll
;             for (int t = 0; t < 8; ++t) { const unsigned long long v = __hip_atomic_load(xch + ((size_t)(u.pm * 256 + row) * 8 + t), __ATOMIC_RELAXED, __HIP_MEMORY_SCOPE_AGENT);
;                 s += __uint_as_float((unsigned)(v & 0xffffffffull)); q += __uint_as_float((unsigned)(v >> 32)); }
;             const float mean = s * (1.0f / DM), var = fmaxf(q * (1.0f / DM) - mean * mean, 0.f);
;             S[row] = (f32x2){mean, 1.0f / sqrtf(var + LN_EPS)}; }
.LBB0_691:
	s_barrier
	s_and_saveexec_b64 s[2:3], s[0:1]
	s_cbranch_execz .LBB0_693
	v_lshlrev_b64 v[0:1], 6, v[162:163]
	v_lshl_add_u64 v[0:1], s[8:9], 0, v[0:1]
	flat_load_dwordx2 v[162:163], v[0:1] sc1
	flat_load_dwordx2 v[168:169], v[0:1] offset:8 sc1
	flat_load_dwordx2 v[170:171], v[0:1] offset:16 sc1
	flat_load_dwordx2 v[172:173], v[0:1] offset:24 sc1
	flat_load_dwordx2 v[174:175], v[0:1] offset:32 sc1
	flat_load_dwordx2 v[176:177], v[0:1] offset:40 sc1
	flat_load_dwordx2 v[178:179], v[0:1] offset:48 sc1
	flat_load_dwordx2 v[180:181], v[0:1] offset:56 sc1
	s_mov_b32 s0, 0x3a000000
	v_lshl_add_u32 v3, v3, 3, 0
	s_waitcnt vmcnt(0) lgkmcnt(0)
	v_add_f32_e32 v164, 0, v162
	v_add_f32_e32 v165, 0, v163
	v_add_f32_e32 v164, v164, v168
	v_add_f32_e32 v165, v165, v169
	v_add_f32_e32 v164, v164, v170
	v_add_f32_e32 v165, v165, v171
	v_add_f32_e32 v164, v164, v172
	v_add_f32_e32 v165, v165, v173
	v_add_f32_e32 v164, v164, v174
	v_add_f32_e32 v165, v165, v175
	v_add_f32_e32 v164, v164, v176
	v_add_f32_e32 v165, v165, v177
	v_add_f32_e32 v162, v164, v178
	v_add_f32_e32 v163, v165, v179
	v_add_f32_e32 v0, v162, v180
	v_mul_f32_e32 v0, 0x3a000000, v0
	v_add_f32_e32 v1, v163, v181
	v_mul_f32_e32 v162, v0, v0
	v_fma_f32 v1, v1, s0, -v162
	v_max_f32_e32 v1, 0, v1
	v_add_f32_e32 v1, 0x3727c5ac, v1
	s_mov_b32 s0, 0xf800000
	v_cmp_gt_f32_e32 vcc, s0, v1
	v_mul_f32_e32 v162, 0x4f800000, v1
	s_nop 0
	v_cndmask_b32_e32 v1, v1, v162, vcc
	v_sqrt_f32_e32 v162, v1
	s_nop 0
	v_add_u32_e32 v163, -1, v162
	v_fma_f32 v164, -v163, v162, v1
	v_cmp_ge_f32_e64 s[0:1], 0, v164
	v_add_u32_e32 v164, 1, v162
	s_nop 0
	v_cndmask_b32_e64 v163, v162, v163, s[0:1]
	v_fma_f32 v162, -v164, v162, v1
	v_cmp_lt_f32_e64 s[0:1], 0, v162
	s_nop 1
	v_cndmask_b32_e64 v162, v163, v164, s[0:1]
	v_mul_f32_e32 v163, 0x37800000, v162
	v_cndmask_b32_e32 v162, v162, v163, vcc
	v_mov_b32_e32 v163, 0x260
	v_cmp_class_f32_e32 vcc, v1, v163
	s_nop 1
	v_cndmask_b32_e32 v1, v162, v1, vcc
	v_div_scale_f32 v162, s[0:1], v1, v1, 1.0
	v_rcp_f32_e32 v163, v162
	s_nop 0
	v_fma_f32 v164, -v162, v163, 1.0
	v_fmac_f32_e32 v163, v164, v163
	v_div_scale_f32 v164, vcc, 1.0, v1, 1.0
	v_mul_f32_e32 v165, v164, v163
	v_fma_f32 v166, -v162, v165, v164
	v_fmac_f32_e32 v165, v166, v163
	v_fma_f32 v162, -v162, v165, v164
	v_div_fmas_f32 v162, v162, v163, v165
	v_div_fixup_f32 v1, v162, v1, 1.0
	ds_write_b64 v3, v[0:1] offset:8192

;     __device__ __forceinline__ void fused(f32x4 (&acc)[2][2][4][2], const pg8::Unit& u, int wr, int wc, int fr, int fq, LAS unsigned char* lds, int wid) const {
;     ...
;         if (lane < 32) { float s = 0.f, q = 0.f;
; #pragma unroll
;             for (int t = 0; t < 8; ++t) { const unsigned long long v = __hip_atomic_load(xch + ((size_t)(u.pm * 256 + row) * 8 + t), __ATOMIC_RELAXED, __HIP_MEMORY_SCOPE_AGENT);
;                 s += __uint_as_float((unsigned)(v & 0xffffffffull)); q += __uint_as_float((unsigned)(v >> 32)); }
;             const float mean = s * (1.0f / DM), var = fmaxf(q * (1.0f / DM) - mean * mean, 0.f);
;             S[row] = (f32x2){mean, 1.0f / sqrtf(var + LN_EPS)}; }
.LBB0_967:
	s_barrier
	s_and_saveexec_b64 s[2:3], s[0:1]
	s_cbranch_execz .LBB0_969
	v_lshlrev_b64 v[36:37], 6, v[36:37]
	v_lshl_add_u64 v[36:37], s[4:5], 0, v[36:37]
	flat_load_dwordx2 v[38:39], v[36:37] sc1
	flat_load_dwordx2 v[140:141], v[36:37] offset:8 sc1
	flat_load_dwordx2 v[142:143], v[36:37] offset:16 sc1
	flat_load_dwordx2 v[148:149], v[36:37] offset:24 sc1
	flat_load_dwordx2 v[150:151], v[36:37] offset:32 sc1
	flat_load_dwordx2 v[154:155], v[36:37] offset:40 sc1
	flat_load_dwordx2 v[174:175], v[36:37] offset:48 sc1
	flat_load_dwordx2 v[178:179], v[36:37] offset:56 sc1
	s_mov_b32 s0, 0x3a000000
	v_lshl_add_u32 v3, v3, 3, 0
	s_waitcnt vmcnt(0) lgkmcnt(0)
	v_add_f32_e32 v132, 0, v38
	v_add_f32_e32 v133, 0, v39
	v_add_f32_e32 v132, v132, v140
	v_add_f32_e32 v133, v133, v141
	v_add_f32_e32 v132, v132, v142
	v_add_f32_e32 v133, v133, v143
	v_add_f32_e32 v132, v132, v148
	v_add_f32_e32 v133, v133, v149
	v_add_f32_e32 v132, v132, v150
	v_add_f32_e32 v133, v133, v151
	v_add_f32_e32 v132, v132, v154
	v_add_f32_e32 v133, v133, v155
	v_add_f32_e32 v38, v132, v174
	v_add_f32_e32 v39, v133, v175
	v_add_f32_e32 v36, v38, v178
	v_mul_f32_e32 v36, 0x3a000000, v36
	v_add_f32_e32 v37, v39, v179
	v_mul_f32_e32 v38, v36, v36
	v_fma_f32 v37, v37, s0, -v38
	v_max_f32_e32 v37, 0, v37
	v_add_f32_e32 v37, 0x3727c5ac, v37
	s_mov_b32 s0, 0xf800000
	v_cmp_gt_f32_e32 vcc, s0, v37
	v_mul_f32_e32 v38, 0x4f800000, v37
	s_nop 0
	v_cndmask_b32_e32 v37, v37, v38, vcc
	v_sqrt_f32_e32 v38, v37
	s_nop 0
	v_add_u32_e32 v39, -1, v38
	v_fma_f32 v132, -v39, v38, v37
	v_cmp_ge_f32_e64 s[0:1], 0, v132
	v_add_u32_e32 v132, 1, v38
	s_nop 0
	v_cndmask_b32_e64 v39, v38, v39, s[0:1]
	v_fma_f32 v38, -v132, v38, v37
	v_cmp_lt_f32_e64 s[0:1], 0, v38
	s_nop 1
	v_cndmask_b32_e64 v38, v39, v132, s[0:1]
	v_mul_f32_e32 v39, 0x37800000, v38
	v_cndmask_b32_e32 v38, v38, v39, vcc
	v_mov_b32_e32 v39, 0x260
	v_cmp_class_f32_e32 vcc, v37, v39
	s_nop 1
	v_cndmask_b32_e32 v37, v38, v37, vcc
	v_div_scale_f32 v38, s[0:1], v37, v37, 1.0
	v_rcp_f32_e32 v39, v38
	s_nop 0
	v_fma_f32 v132, -v38, v39, 1.0
	v_fmac_f32_e32 v39, v132, v39
	v_div_scale_f32 v132, vcc, 1.0, v37, 1.0
	v_mul_f32_e32 v133, v132, v39
	v_fma_f32 v134, -v38, v133, v132
	v_fmac_f32_e32 v133, v134, v39
	v_fma_f32 v38, -v38, v133, v132
	v_div_fmas_f32 v38, v38, v39, v133
	v_div_fixup_f32 v37, v38, v37, 1.0
	ds_write_b64 v3, v[36:37] offset:8192
